# cross-attention main loop: K and V LDS reads hoisted ahead of their MFMAs (15 in flight), waits recomputed, MFMA dependency pads re-derived
# speedup vs baseline: 1.0076x; 1.0075x over previous
; template <int DQK, int DV, bool CAUSAL, bool MLA> ...
;     ...
;         if (kt + 1 < nkt) ATT_PREFETCH(kt + 1);
;         const int qw0 = q0 + wv * 16;
;         if (CAUSAL && 64 * kt > qw0 + 15) continue;
;         f32x4 sT[4];
; #pragma unroll
;         for (int k4 = 0; k4 < 4; ++k4) { sT[k4] = (f32x4){0.f, 0.f, 0.f, 0.f};
; #pragma unroll
;             for (int ks = 0; ks < NKS; ++ks) { const bf16x8 a = *(const bf16x8*)(Ks + (16 * k4 + j) * KS + (32 * ks + 8 * g) * 2);
;                 sT[k4] = __builtin_amdgcn_mfma_f32_16x16x32_bf16(a, qf[ks], sT[k4], 0, 0, 0); } }
;         if (CAUSAL && 64 * kt + 63 > qw0) {
; #pragma unroll
;             for (int k4 = 0; k4 < 4; ++k4)
; #pragma unroll
;                 for (int r = 0; r < 4; ++r) if (64 * kt + 16 * k4 + 4 * g + r > qrow) sT[k4][r] = -INFINITY;
;         }
;         float mx = -INFINITY;
; #pragma unroll
;         for (int k4 = 0; k4 < 4; ++k4) mx = fmaxf(mx, fmaxf(fmaxf(sT[k4][0], sT[k4][1]), fmaxf(sT[k4][2], sT[k4][3])));
;         mx = fmaxf(mx, __shfl_xor(mx, 16)); mx = fmaxf(mx, __shfl_xor(mx, 32));
.LBB0_2226:
	s_or_b64 exec, exec, s[10:11]
	ds_read_b128 v[188:191], v82
	ds_read_b128 v[192:195], v82 offset:64
	ds_read_b128 v[196:199], v82 offset:128
	ds_read_b128 v[200:203], v82 offset:192
	ds_read_b128 v[204:207], v82 offset:4352
	ds_read_b128 v[208:211], v82 offset:4416
	ds_read_b128 v[212:215], v82 offset:4480
	ds_read_b128 v[216:219], v82 offset:4544
	ds_read_b128 v[220:223], v82 offset:8704
	ds_read_b128 v[224:227], v82 offset:8768
	ds_read_b128 v[228:231], v82 offset:8832
	ds_read_b128 v[232:235], v82 offset:8896
	ds_read_b128 v[236:239], v82 offset:13056
	ds_read_b128 v[240:243], v82 offset:13120
	ds_read_b128 v[244:247], v82 offset:13184
	s_mov_b32 s10, 0xff800000
	v_lshl_add_u64 v[24:25], v[76:77], 0, s[4:5]
	v_lshl_add_u64 v[28:29], v[74:75], 0, s[4:5]
	global_load_dwordx4 v[24:27], v[24:25], off
	s_add_u32 s4, s4, 0x80
	global_load_dwordx4 v[28:31], v[28:29], off
	s_addc_u32 s5, s5, 0
	s_waitcnt lgkmcnt(14)
	v_mfma_f32_16x16x32_bf16 v[84:87], v[188:191], v[4:7], 0
	ds_read_b128 v[248:251], v82 offset:13248
	s_cmpk_eq_i32 s4, 0x200
	s_waitcnt lgkmcnt(14)
	v_mfma_f32_16x16x32_bf16 v[84:87], v[192:195], v[8:11], v[84:87]
	s_waitcnt lgkmcnt(13)
	v_mfma_f32_16x16x32_bf16 v[84:87], v[196:199], v[12:15], v[84:87]
	s_waitcnt lgkmcnt(12)
	v_mfma_f32_16x16x32_bf16 v[84:87], v[200:203], v[16:19], v[84:87]
	s_nop 6
	s_nop 0
	v_max_f32_e32 v65, v87, v87
	v_max_f32_e32 v66, v86, v86
	v_max_f32_e32 v65, v66, v65
	s_waitcnt lgkmcnt(11)
	v_mfma_f32_16x16x32_bf16 v[100:103], v[204:207], v[4:7], 0
	v_max3_f32 v65, v84, v85, v65
	s_waitcnt lgkmcnt(10)
	v_mfma_f32_16x16x32_bf16 v[100:103], v[208:211], v[8:11], v[100:103]
	s_waitcnt lgkmcnt(9)
	v_mfma_f32_16x16x32_bf16 v[100:103], v[212:215], v[12:15], v[100:103]
	s_waitcnt lgkmcnt(8)
	v_mfma_f32_16x16x32_bf16 v[102:105], v[216:219], v[16:19], v[100:103]
	s_nop 6
	s_nop 0
	v_max_f32_e32 v66, v105, v105
	s_waitcnt lgkmcnt(7)
	v_mfma_f32_16x16x32_bf16 v[106:109], v[220:223], v[4:7], 0
	v_max_f32_e32 v67, v104, v104
	v_max_f32_e32 v66, v67, v66
	v_max3_f32 v66, v102, v103, v66
	s_waitcnt lgkmcnt(6)
	v_mfma_f32_16x16x32_bf16 v[106:109], v[224:227], v[8:11], v[106:109]
	v_max3_f32 v65, v65, s10, v66
	s_mov_b64 s[10:11], 0x10000
	s_waitcnt lgkmcnt(5)
	v_mfma_f32_16x16x32_bf16 v[106:109], v[228:231], v[12:15], v[106:109]
	v_lshl_add_u64 v[70:71], v[70:71], 0, s[10:11]
	v_lshl_add_u64 v[72:73], v[72:73], 0, s[10:11]
	s_waitcnt lgkmcnt(4)
	v_mfma_f32_16x16x32_bf16 v[106:109], v[232:235], v[16:19], v[106:109]
	s_nop 6
	s_nop 0
	v_max_f32_e32 v66, v109, v109
	s_waitcnt lgkmcnt(3)
	v_mfma_f32_16x16x32_bf16 v[110:113], v[236:239], v[4:7], 0
	v_max_f32_e32 v67, v108, v108
	v_max_f32_e32 v66, v67, v66
	v_max3_f32 v66, v106, v107, v66
	s_waitcnt lgkmcnt(2)
	v_mfma_f32_16x16x32_bf16 v[110:113], v[240:243], v[8:11], v[110:113]
	s_waitcnt lgkmcnt(1)
	v_mfma_f32_16x16x32_bf16 v[110:113], v[244:247], v[12:15], v[110:113]
	s_waitcnt lgkmcnt(0)
	v_mfma_f32_16x16x32_bf16 v[110:113], v[248:251], v[16:19], v[110:113]
	s_nop 7
	v_max_f32_e32 v67, v113, v113
	v_max_f32_e32 v78, v112, v112
	v_max_f32_e32 v67, v78, v67
	v_max3_f32 v67, v110, v111, v67
	v_max3_f32 v65, v65, v66, v67
	ds_bpermute_b32 v66, v80, v65
	s_waitcnt lgkmcnt(0)
	v_max_f32_e32 v66, v66, v66
	v_max_f32_e32 v65, v65, v66
	ds_bpermute_b32 v66, v81, v65
	s_waitcnt lgkmcnt(0)
; __device__ __forceinline__ u32x4 pk8(f32x4 a, f32x4 b) { u32x4 w; w.x = pk2(a.x, a.y); w.y = pk2(a.z, a.w); w.z = pk2(b.x, b.y); w.w = pk2(b.z, b.w); return w; }
; template <int DQK, int DV, bool CAUSAL, bool MLA> ...
;     ...
;         const float mnew = fmaxf(mrun, mx); const float alpha = __builtin_amdgcn_exp2f(mrun - mnew); mrun = mnew;
;         float psum = 0.f;
; #pragma unroll
;         for (int k4 = 0; k4 < 4; ++k4)
; #pragma unroll
;             for (int r = 0; r < 4; ++r) { const float pv = __builtin_amdgcn_exp2f(sT[k4][r] - mnew); sT[k4][r] = pv; psum += pv; }
;         lsum = lsum * alpha + psum;
; #pragma unroll
;         for (int d = 0; d < NDT; ++d) oT[d] *= alpha;
; #pragma unroll
;         for (int kc = 0; kc < 2; ++kc) {
;             const bf16x8 pb = __builtin_bit_cast(bf16x8, pk8(sT[2 * kc], sT[2 * kc + 1]));
; #pragma unroll
;             for (int d = 0; d < NDT; ++d) { const unsigned char* vp = Vs + (16 * d + j) * VS + (32 * kc + 4 * g) * 2;
;                 const u32x2 lo = *(const u32x2*)vp, hi = *(const u32x2*)(vp + 32); u32x4 w; w.x = lo.x; w.y = lo.y; w.z = hi.x; w.w = hi.y;
;                 oT[d] = __builtin_amdgcn_mfma_f32_16x16x32_bf16(__builtin_bit_cast(bf16x8, w), pb, oT[d], 0, 0, 0); }
;         }
	v_max3_f32 v100, v64, v65, v66
	v_add_u32_e32 v118, 0x4000, v97
	v_add_u32_e32 v119, 0x4000, v98
	v_add_u32_e32 v120, 0x7000, v97
	v_add_u32_e32 v121, 0x8000, v97
	v_add_u32_e32 v122, 0x4800, v98
	v_add_u32_e32 v123, 0x5000, v98
	v_add_u32_e32 v124, 0x6800, v97
	v_add_u32_e32 v125, 0x7800, v97
	ds_read2_b64 v[188:191], v118 offset0:128 offset1:132
	ds_read2_b64 v[192:195], v119 offset0:128 offset1:132
	ds_read2_b64 v[196:199], v122 offset0:160 offset1:164
	ds_read2_b64 v[200:203], v123 offset0:192 offset1:196
	ds_read2_b64 v[204:207], v124 offset1:4
	ds_read2_b64 v[208:211], v120 offset0:32 offset1:36
	ds_read2_b64 v[212:215], v125 offset0:64 offset1:68
	ds_read2_b64 v[216:219], v121 offset0:96 offset1:100
	ds_read2_b64 v[220:223], v118 offset0:136 offset1:140
	ds_read2_b64 v[224:227], v122 offset0:168 offset1:172
	ds_read2_b64 v[228:231], v123 offset0:200 offset1:204
	ds_read2_b64 v[232:235], v124 offset0:8 offset1:12
	ds_read2_b64 v[236:239], v120 offset0:40 offset1:44
	ds_read2_b64 v[240:243], v125 offset0:72 offset1:76
	ds_read2_b64 v[244:247], v119 offset0:136 offset1:140
	v_sub_f32_e32 v64, v64, v100
	v_exp_f32_e32 v78, v64
	v_sub_f32_e32 v64, v84, v100
	v_exp_f32_e32 v83, v64
	v_sub_f32_e32 v65, v85, v100
	v_exp_f32_e32 v88, v65
	v_sub_f32_e32 v65, v86, v100
	v_exp_f32_e32 v89, v65
	v_sub_f32_e32 v65, v87, v100
	v_exp_f32_e32 v90, v65
	v_sub_f32_e32 v65, v102, v100
	v_add_f32_e32 v64, 0, v83
	v_exp_f32_e32 v101, v65
	v_sub_f32_e32 v65, v103, v100
	v_add_f32_e32 v64, v88, v64
	v_exp_f32_e32 v102, v65
	v_sub_f32_e32 v65, v104, v100
	v_add_f32_e32 v64, v89, v64
	v_exp_f32_e32 v103, v65
	v_sub_f32_e32 v65, v105, v100
	v_add_f32_e32 v64, v90, v64
	v_exp_f32_e32 v104, v65
	v_sub_f32_e32 v65, v106, v100
	v_add_f32_e32 v64, v101, v64
	v_exp_f32_e32 v114, v65
	v_sub_f32_e32 v65, v107, v100
	v_add_f32_e32 v64, v102, v64
	v_exp_f32_e32 v115, v65
	v_sub_f32_e32 v65, v108, v100
	v_add_f32_e32 v64, v103, v64
	v_exp_f32_e32 v116, v65
	v_sub_f32_e32 v65, v109, v100
	v_add_f32_e32 v64, v104, v64
	v_exp_f32_e32 v117, v65
	v_add_f32_e32 v64, v114, v64
	v_add_f32_e32 v64, v115, v64
	v_add_f32_e32 v64, v116, v64
	v_add_f32_e32 v79, v117, v64
	v_sub_f32_e32 v64, v110, v100
	v_exp_f32_e32 v110, v64
	v_sub_f32_e32 v64, v111, v100
	v_exp_f32_e32 v111, v64
	v_sub_f32_e32 v64, v112, v100
	v_exp_f32_e32 v112, v64
	v_sub_f32_e32 v64, v113, v100
	v_pk_mul_f32 v[84:85], v[36:37], v[78:79] op_sel_hi:[1,0]
	v_cvt_pk_bf16_f32 v37, v89, v90
	v_exp_f32_e32 v113, v64
	v_pk_mul_f32 v[66:67], v[34:35], v[78:79] op_sel_hi:[1,0]
	v_pk_mul_f32 v[64:65], v[32:33], v[78:79] op_sel_hi:[1,0]
	v_pk_mul_f32 v[34:35], v[62:63], v[78:79] op_sel_hi:[1,0]
	v_pk_mul_f32 v[32:33], v[60:61], v[78:79] op_sel_hi:[1,0]
	v_add_f32_e32 v36, v110, v79
	v_add_f32_e32 v36, v111, v36
	v_add_f32_e32 v36, v112, v36
	v_pk_mul_f32 v[86:87], v[38:39], v[78:79] op_sel_hi:[1,0]
	v_pk_mul_f32 v[42:43], v[42:43], v[78:79] op_sel_hi:[1,0]
	v_pk_mul_f32 v[40:41], v[40:41], v[78:79] op_sel_hi:[1,0]
	v_pk_mul_f32 v[46:47], v[46:47], v[78:79] op_sel_hi:[1,0]
	v_pk_mul_f32 v[44:45], v[44:45], v[78:79] op_sel_hi:[1,0]
	v_pk_mul_f32 v[50:51], v[50:51], v[78:79] op_sel_hi:[1,0]
	v_pk_mul_f32 v[48:49], v[48:49], v[78:79] op_sel_hi:[1,0]
	v_pk_mul_f32 v[54:55], v[54:55], v[78:79] op_sel_hi:[1,0]
	v_pk_mul_f32 v[52:53], v[52:53], v[78:79] op_sel_hi:[1,0]
	v_pk_mul_f32 v[58:59], v[58:59], v[78:79] op_sel_hi:[1,0]
	v_pk_mul_f32 v[56:57], v[56:57], v[78:79] op_sel_hi:[1,0]
	v_add_f32_e32 v79, v113, v36
	v_cvt_pk_bf16_f32 v36, v83, v88
	v_cvt_pk_bf16_f32 v38, v101, v102
	v_cvt_pk_bf16_f32 v39, v103, v104
	s_waitcnt lgkmcnt(14)
	s_nop 0
	v_mfma_f32_16x16x32_bf16 v[102:105], v[188:191], v[36:39], v[64:67]
	ds_read2_b64 v[248:251], v121 offset0:104 offset1:108
	v_fmac_f32_e32 v79, v99, v78
	s_waitcnt lgkmcnt(14)
	v_mfma_f32_16x16x32_bf16 v[106:109], v[192:195], v[36:39], v[84:87]
	s_nop 2
	s_waitcnt lgkmcnt(13)
	v_mfma_f32_16x16x32_bf16 v[40:43], v[196:199], v[36:39], v[40:43]
	s_waitcnt lgkmcnt(12)
	v_mfma_f32_16x16x32_bf16 v[44:47], v[200:203], v[36:39], v[44:47]
	v_cvt_pk_bf16_f32 v64, v114, v115
	v_cvt_pk_bf16_f32 v65, v116, v117
	s_waitcnt lgkmcnt(11)
	v_mfma_f32_16x16x32_bf16 v[48:51], v[204:207], v[36:39], v[48:51]
	v_cvt_pk_bf16_f32 v66, v110, v111
	v_cvt_pk_bf16_f32 v67, v112, v113
	s_waitcnt lgkmcnt(10)
	v_mfma_f32_16x16x32_bf16 v[52:55], v[208:211], v[36:39], v[52:55]
	s_waitcnt lgkmcnt(9)
	v_mfma_f32_16x16x32_bf16 v[56:59], v[212:215], v[36:39], v[56:59]
	s_waitcnt lgkmcnt(8)
	v_mfma_f32_16x16x32_bf16 v[60:63], v[216:219], v[36:39], v[32:35]
	s_nop 2
	s_waitcnt lgkmcnt(7)
	v_mfma_f32_16x16x32_bf16 v[32:35], v[220:223], v[64:67], v[102:105]
	s_nop 2
	s_waitcnt lgkmcnt(6)
	v_mfma_f32_16x16x32_bf16 v[40:43], v[224:227], v[64:67], v[40:43]
	s_waitcnt lgkmcnt(5)
	v_mfma_f32_16x16x32_bf16 v[44:47], v[228:231], v[64:67], v[44:47]
	s_waitcnt lgkmcnt(4)
	v_mfma_f32_16x16x32_bf16 v[48:51], v[232:235], v[64:67], v[48:51]
	s_waitcnt lgkmcnt(3)
	v_mfma_f32_16x16x32_bf16 v[52:55], v[236:239], v[64:67], v[52:55]
	s_waitcnt lgkmcnt(2)
	v_mfma_f32_16x16x32_bf16 v[56:59], v[240:243], v[64:67], v[56:59]
	s_waitcnt lgkmcnt(1)
	v_mfma_f32_16x16x32_bf16 v[36:39], v[244:247], v[64:67], v[106:109]
	s_waitcnt lgkmcnt(0)
	v_mfma_f32_16x16x32_bf16 v[60:63], v[248:251], v[64:67], v[60:63]
	v_add_u32_e32 v89, 0x4000, v97
	v_add_u32_e32 v88, 0x4000, v98
	v_add_u32_e32 v83, 0x7000, v97
	v_add_u32_e32 v90, 0x8000, v97
	v_add_u32_e32 v86, 0x4800, v98
	v_add_u32_e32 v85, 0x5000, v98
	v_add_u32_e32 v84, 0x6800, v97
	v_add_u32_e32 v87, 0x7800, v97
	s_cbranch_scc1 .LBB0_2228
	v_mov_b32_e32 v99, v79
	v_mov_b32_e32 v64, v100
	s_branch .LBB0_2218
